# scan slice waves at s_setprio 2 (state recurrence is the chain critical path)
# speedup vs baseline: 1.0139x; 1.0139x over previous
; __device__ __forceinline__ float bflo(unsigned w) { return __uint_as_float(w << 16); }
; __device__ __forceinline__ float bfhi(unsigned w) { return __uint_as_float(w & 0xffff0000u); }
; __device__ __forceinline__ f32x4 mfma16(bf16x8 a, bf16x8 b, f32x4 c) { return __builtin_amdgcn_mfma_f32_16x16x32_bf16(a, b, c, 0, 0, 0); }
; __device__ __forceinline__ bf16x8 pack8(f32x4 a, f32x4 b) { v4u w; w.x = pk2(a[0], a[1]); w.y = pk2(a[2], a[3]); w.z = pk2(b[0], b[1]); w.w = pk2(b[2], b[3]); return __builtin_bit_cast(bf16x8, w); }
; __device__ __forceinline__ void scan_chain(const Params& P, bool smp, int s, int h, int sl, int lane) {
;     const int l15 = lane & 15, q4 = lane >> 4, e = 16 * sl + l15;
;     const int cu0 = smp ? 1024 + s : s * 128, nsteps = smp ? 1 : 128;
;     f32x4 S[4];
; #pragma unroll
;     for (int tau = 0; tau < 4; ++tau)
; #pragma unroll
;         for (int r = 0; r < 4; ++r) S[tau][r] = smp ? P.state_gdn[(((size_t)s * 8 + h) * 64 + 16 * tau + 4 * q4 + r) * 64 + e] : 0.f;
;     const float* GT = (const float*)(P.ws + WS_GT);
;     float* OA = (float*)((unsigned char*)P.out + YO_OA); float* OAS = (float*)(P.ws + WS_OAS);
; #pragma unroll 1
;     for (int n = 0; n < nsteps; ++n) {
;         const int cu = cu0 + n; const unsigned char* ops = P.ws + WS_OPS + ((size_t)cu * 8 + h) * OPS_UNIT;
;         const float gt = GT[cu * 8 + h];
;         const bf16x8* Wf = (const bf16x8*)(ops + OPS_W) + lane; const bf16x8* KT = (const bf16x8*)(ops + OPS_KT) + lane;
;         const bf16x8* QD = (const bf16x8*)(ops + OPS_QD) + lane; const bf16x8* QK = (const bf16x8*)(ops + OPS_QK) + lane;
;         const v2u* Up = (const v2u*)(ops + OPS_U) + (sl * 4) * 64 + lane;
;         bf16x8 Sb[2]; Sb[0] = pack8(S[0], S[1]); Sb[1] = pack8(S[2], S[3]);
;         f32x4 vn[4];
; #pragma unroll
;         for (int tau = 0; tau < 4; ++tau) { f32x4 av = {0.f, 0.f, 0.f, 0.f}; av = mfma16(Wf[(2 * tau) * 64], Sb[0], av); av = mfma16(Wf[(2 * tau + 1) * 64], Sb[1], av);
;             const v2u ub = Up[tau * 64]; const f32x4 u = {bflo(ub.x), bfhi(ub.x), bflo(ub.y), bfhi(ub.y)}; vn[tau] = u - av; }
.LBB0_639:
	v_readlane_b32 s18, v247, 0
	v_readlane_b32 s19, v247, 1
	s_add_u32 s29, s18, 0x1400000
	s_addc_u32 s30, s19, 0
	s_ashr_i32 s8, s96, 3
	s_lshl_b32 s0, s8, 7
	s_ashr_i32 s1, s0, 31
	s_and_b32 s2, s96, 7
	s_lshl_b64 s[14:15], s[0:1], 3
	s_add_u32 s10, s18, 0x3600000
	s_addc_u32 s11, s19, 0
	s_add_u32 s4, s18, 0xb700000
	s_addc_u32 s5, s19, 0
	s_ashr_i32 s9, s8, 31
	s_add_u32 s22, s18, 0x23900000
	s_addc_u32 s23, s19, 0
	s_or_b32 s12, s14, s2
	s_mul_i32 s13, s15, 0xa000
	s_mul_hi_u32 s16, s12, 0xa000
	s_add_i32 s16, s16, s13
	s_mul_i32 s12, s12, 0xa000
	s_add_u32 s12, s22, s12
	s_addc_u32 s13, s23, s16
	s_add_u32 s16, s18, 0x3d300000
	s_addc_u32 s17, s19, 0
	s_lshl_b32 s28, s96, 1
	s_ashr_i32 s18, s40, 8
	s_add_i32 s18, s18, s28
	s_ashr_i32 s26, s18, 3
	s_ashr_i32 s27, s26, 31
	s_and_b32 s34, s18, 7
	v_lshrrev_b32_e32 v1, 4, v164
	s_lshl_b64 s[18:19], s[26:27], 9
	v_and_b32_e32 v30, 15, v35
	v_lshl_or_b32 v2, v1, 2, s18
	s_bfe_u32 s24, s40, 0x20006
	v_lshl_or_b32 v2, s34, 6, v2
	v_mov_b32_e32 v3, s19
	v_lshlrev_b32_e32 v4, 2, v30
	v_mov_b32_e32 v165, 0
	v_lshl_or_b32 v4, s24, 6, v4
	v_mov_b32_e32 v5, v165
	v_lshlrev_b64 v[2:3], 8, v[2:3]
	v_lshl_add_u64 v[14:15], s[74:75], 0, v[4:5]
	v_or_b32_e32 v10, 0x1100, v2
	v_mov_b32_e32 v11, v3
	v_or_b32_e32 v8, 0x1000, v2
	v_mov_b32_e32 v9, v3
	v_lshl_add_u64 v[16:17], v[14:15], 0, v[10:11]
	v_or_b32_e32 v10, 0x1200, v2
	v_lshl_add_u64 v[6:7], v[14:15], 0, v[2:3]
	v_lshl_add_u64 v[8:9], v[14:15], 0, v[8:9]
	v_lshl_add_u64 v[18:19], v[14:15], 0, v[10:11]
	v_or_b32_e32 v10, 0x1300, v2
	s_add_i32 s18, s26, 0x400
	v_lshl_add_u64 v[20:21], v[14:15], 0, v[10:11]
	global_load_dword v10, v[6:7], off
	global_load_dword v11, v[6:7], off offset:256
	global_load_dword v12, v[6:7], off offset:512
	global_load_dword v13, v[6:7], off offset:768
	s_nop 0
	global_load_dword v6, v[8:9], off
	global_load_dword v7, v[16:17], off
	s_nop 0
	global_load_dword v8, v[18:19], off
	global_load_dword v9, v[20:21], off
	v_or_b32_e32 v18, 0x2100, v2
	v_mov_b32_e32 v19, v3
	s_ashr_i32 s19, s18, 31
	v_lshl_add_u64 v[22:23], v[14:15], 0, v[18:19]
	v_or_b32_e32 v18, 0x2200, v2
	s_lshl_b64 s[20:21], s[18:19], 3
	v_lshl_add_u64 v[28:29], v[14:15], 0, v[18:19]
	v_or_b32_e32 v18, 0x2300, v2
	s_or_b32 s19, s20, s34
	v_lshl_add_u64 v[32:33], v[14:15], 0, v[18:19]
	v_or_b32_e32 v18, 0x3000, v2
	s_mul_i32 s20, s21, 0xa000
	s_mul_hi_u32 s21, s19, 0xa000
	v_lshl_add_u64 v[36:37], v[14:15], 0, v[18:19]
	v_or_b32_e32 v18, 0x3100, v2
	s_add_i32 s21, s21, s20
	s_mul_i32 s19, s19, 0xa000
	v_or_b32_e32 v16, 0x2000, v2
	v_mov_b32_e32 v17, v3
	v_lshl_add_u64 v[38:39], v[14:15], 0, v[18:19]
	v_or_b32_e32 v18, 0x3200, v2
	s_add_u32 s20, s22, s19
	v_lshl_add_u64 v[16:17], v[14:15], 0, v[16:17]
	v_lshl_add_u64 v[40:41], v[14:15], 0, v[18:19]
	v_or_b32_e32 v2, 0x3300, v2
	s_addc_u32 s21, s23, s21
	v_lshlrev_b32_e32 v18, 4, v164
	v_lshl_add_u64 v[2:3], v[14:15], 0, v[2:3]
	global_load_dwordx4 v[24:27], v18, s[20:21]
	global_load_dword v20, v[16:17], off
	global_load_dword v21, v[22:23], off
	s_nop 0
	global_load_dword v22, v[28:29], off
	global_load_dword v23, v[32:33], off
	global_load_dword v14, v[36:37], off
	global_load_dword v15, v[38:39], off
	global_load_dword v16, v[40:41], off
	global_load_dword v17, v[2:3], off
	s_lshl_b32 s18, s18, 3
	global_load_dwordx4 v[36:39], v18, s[20:21] offset:1024
	global_load_dwordx4 v[40:43], v18, s[20:21] offset:2048
	s_or_b32 s18, s18, s34
	s_ashr_i32 s19, s18, 31
	s_lshl_b64 s[18:19], s[18:19], 2
	s_add_u32 s18, s29, s18
	s_addc_u32 s19, s30, s19
	s_lshl_b32 s22, s24, 11
	s_add_u32 s22, s20, s22
	s_addc_u32 s23, s21, 0
	v_lshlrev_b32_e32 v2, 3, v164
	v_mov_b32_e32 v3, v165
	v_lshl_add_u64 v[32:33], s[22:23], 0, v[2:3]
	s_mov_b32 s31, 0x8000
	v_mov_b32_e32 v19, v165
	v_add_co_u32_e32 v44, vcc, s31, v32
	s_movk_i32 s36, 0x2000
	v_lshl_add_u64 v[28:29], s[20:21], 0, v[18:19]
	v_addc_co_u32_e32 v45, vcc, 0, v33, vcc
	v_add_co_u32_e32 v82, vcc, s36, v28
	global_load_dwordx2 v[96:97], v[44:45], off
	s_nop 0
	global_load_dwordx4 v[44:47], v18, s[20:21] offset:3072
	v_addc_co_u32_e32 v83, vcc, 0, v29, vcc
	global_load_dwordx4 v[48:51], v[82:83], off offset:-4096
	s_movk_i32 s35, 0x1000
	v_add_co_u32_e32 v60, vcc, s35, v28
	s_mov_b64 s[24:25], 0x8000
	s_nop 0
	v_addc_co_u32_e32 v61, vcc, 0, v29, vcc
	global_load_dwordx4 v[52:55], v[60:61], off offset:1024
	v_lshl_add_u64 v[32:33], v[32:33], 0, s[24:25]
	global_load_dwordx2 v[98:99], v[32:33], off offset:512
	global_load_dwordx4 v[56:59], v[60:61], off offset:2048
	s_nop 0
	global_load_dwordx4 v[60:63], v[60:61], off offset:3072
	s_movk_i32 s22, 0x4000
	s_mov_b64 s[20:21], 0x4000
	v_add_co_u32_e32 v64, vcc, s22, v28
	v_lshl_add_u64 v[68:69], v[28:29], 0, s[20:21]
	s_nop 0
	v_addc_co_u32_e32 v65, vcc, 0, v29, vcc
	s_movk_i32 s20, 0x6000
	v_add_co_u32_e32 v72, vcc, s20, v28
	global_load_dwordx4 v[64:67], v[64:65], off
	s_nop 0
	v_addc_co_u32_e32 v73, vcc, 0, v29, vcc
	global_load_dwordx4 v[68:71], v[68:69], off offset:1024
	s_nop 0
	global_load_dwordx4 v[72:75], v[72:73], off
	s_nop 0
	global_load_dwordx2 v[100:101], v[32:33], off offset:1024
	s_nop 0
	global_load_dwordx2 v[32:33], v[32:33], off offset:1536
	s_nop 0
	global_load_dword v34, v165, s[18:19]
	s_waitcnt vmcnt(30)
	v_cvt_pk_bf16_f32 v76, v10, v11
	s_waitcnt vmcnt(28)
	v_cvt_pk_bf16_f32 v77, v12, v13
	s_waitcnt vmcnt(26)
	v_cvt_pk_bf16_f32 v78, v6, v7
	s_waitcnt vmcnt(24)
	v_cvt_pk_bf16_f32 v79, v8, v9
	s_mov_b64 s[18:19], 0x2000
	v_lshl_add_u64 v[92:93], v[28:29], 0, s[18:19]
	s_waitcnt vmcnt(23)
	v_mfma_f32_16x16x32_bf16 v[24:27], v[24:27], v[76:79], 0
	global_load_dwordx4 v[84:87], v[82:83], off
	global_load_dwordx4 v[88:91], v[92:93], off offset:1024
	s_waitcnt vmcnt(23)
; __device__ __forceinline__ float bflo(unsigned w) { return __uint_as_float(w << 16); }
; __device__ __forceinline__ float bfhi(unsigned w) { return __uint_as_float(w & 0xffff0000u); }
; __device__ __forceinline__ f32x4 mfma16(bf16x8 a, bf16x8 b, f32x4 c) { return __builtin_amdgcn_mfma_f32_16x16x32_bf16(a, b, c, 0, 0, 0); }
; __device__ __forceinline__ bf16x8 pack8(f32x4 a, f32x4 b) { v4u w; w.x = pk2(a[0], a[1]); w.y = pk2(a[2], a[3]); w.z = pk2(b[0], b[1]); w.w = pk2(b[2], b[3]); return __builtin_bit_cast(bf16x8, w); }
; __device__ __forceinline__ void scan_chain(const Params& P, bool smp, int s, int h, int sl, int lane) {
;     ...
;         bf16x8 Sb[2]; Sb[0] = pack8(S[0], S[1]); Sb[1] = pack8(S[2], S[3]);
;         f32x4 vn[4];
; #pragma unroll
;         for (int tau = 0; tau < 4; ++tau) { f32x4 av = {0.f, 0.f, 0.f, 0.f}; av = mfma16(Wf[(2 * tau) * 64], Sb[0], av); av = mfma16(Wf[(2 * tau + 1) * 64], Sb[1], av);
;             const v2u ub = Up[tau * 64]; const f32x4 u = {bflo(ub.x), bfhi(ub.x), bflo(ub.y), bfhi(ub.y)}; vn[tau] = u - av; }
;         bf16x8 Vb[2]; Vb[0] = pack8(vn[0], vn[1]); Vb[1] = pack8(vn[2], vn[3]);
;         f32x4 ao[4];
; #pragma unroll
;         for (int tau = 0; tau < 4; ++tau) { f32x4 a = {0.f, 0.f, 0.f, 0.f}; a = mfma16(QD[(2 * tau) * 64], Sb[0], a); a = mfma16(QD[(2 * tau + 1) * 64], Sb[1], a);
;             a = mfma16(QK[((tau < 2) ? tau : 2 * tau - 2) * 64], Vb[0], a); if (tau >= 2) a = mfma16(QK[(2 * tau - 1) * 64], Vb[1], a); ao[tau] = a; }
; #pragma unroll
;         for (int tau = 0; tau < 4; ++tau) { f32x4 a = S[tau] * gt; a = mfma16(KT[(2 * tau) * 64], Vb[0], a); a = mfma16(KT[(2 * tau + 1) * 64], Vb[1], a); S[tau] = a; }
;         if (!smp) { float* op = OA + ((size_t)s * TP + n * 64) * 512 + h * 64 + e;
; #pragma unroll
;             for (int tau = 0; tau < 4; ++tau)
; #pragma unroll
;                 for (int r = 0; r < 4; ++r) op[(size_t)(16 * tau + 4 * q4 + r) * 512] = ao[tau][r];
;         } else { float* op = OAS + ((size_t)s * 16) * 512 + h * 64 + e;
; #pragma unroll
;             for (int r = 0; r < 4; ++r) op[(size_t)(4 * q4 + r) * 512] = ao[0][r]; }
;     }
;     float* so = P.out + (smp ? O_GS : O_GP) + (((size_t)s * 8 + h) * 64) * 64 + e;
; #pragma unroll
;     for (int tau = 0; tau < 4; ++tau)
; #pragma unroll
;         for (int r = 0; r < 4; ++r) so[(size_t)(16 * tau + 4 * q4 + r) * 64] = S[tau][r];
	v_cvt_pk_bf16_f32 v80, v20, v21
	s_waitcnt vmcnt(21)
	v_cvt_pk_bf16_f32 v81, v22, v23
	s_waitcnt vmcnt(15)
	v_mfma_f32_16x16x32_bf16 v[40:43], v[40:43], v[76:79], 0
	v_cvt_pk_bf16_f32 v82, v14, v15
	v_cvt_pk_bf16_f32 v83, v16, v17
	s_movk_i32 s18, 0x3000
	v_readlane_b32 s72, v247, 7
	v_mfma_f32_16x16x32_bf16 v[24:27], v[36:39], v[80:83], v[24:27]
	global_load_dwordx4 v[36:39], v[92:93], off offset:2048
	v_readlane_b32 s82, v247, 17
	global_load_dwordx4 v[92:95], v[92:93], off offset:3072
	s_waitcnt vmcnt(15)
	v_mfma_f32_16x16x32_bf16 v[40:43], v[44:47], v[80:83], v[40:43]
	v_lshlrev_b32_e32 v19, 16, v96
	v_and_b32_e32 v31, 0xffff0000, v96
	s_nop 0
	v_sub_f32_e32 v31, v31, v25
	s_waitcnt vmcnt(14)
	v_mfma_f32_16x16x32_bf16 v[44:47], v[48:51], v[76:79], 0
	v_lshlrev_b32_e32 v48, 16, v97
	v_and_b32_e32 v49, 0xffff0000, v97
	v_sub_f32_e32 v96, v49, v27
	s_waitcnt vmcnt(13)
	v_mfma_f32_16x16x32_bf16 v[44:47], v[52:55], v[80:83], v[44:47]
	v_sub_f32_e32 v52, v48, v26
	v_sub_f32_e32 v19, v19, v24
	s_waitcnt vmcnt(12)
	v_lshlrev_b32_e32 v53, 16, v98
	s_waitcnt vmcnt(11)
	v_mfma_f32_16x16x32_bf16 v[24:27], v[56:59], v[76:79], 0
	v_and_b32_e32 v54, 0xffff0000, v98
	v_lshlrev_b32_e32 v48, 16, v99
	v_sub_f32_e32 v53, v53, v40
	s_waitcnt vmcnt(10)
	v_mfma_f32_16x16x32_bf16 v[24:27], v[60:63], v[80:83], v[24:27]
	v_cvt_pk_bf16_f32 v40, v19, v31
	v_sub_f32_e32 v55, v48, v42
	s_waitcnt vmcnt(6)
	v_lshlrev_b32_e32 v19, 16, v100
	v_and_b32_e32 v31, 0xffff0000, v100
	v_sub_f32_e32 v42, v54, v41
	v_sub_f32_e32 v31, v31, v45
	v_sub_f32_e32 v19, v19, v44
	v_cvt_pk_bf16_f32 v41, v52, v96
	v_cvt_pk_bf16_f32 v42, v53, v42
	v_lshlrev_b32_e32 v52, 16, v101
	v_and_b32_e32 v53, 0xffff0000, v101
	v_cvt_pk_bf16_f32 v44, v19, v31
	s_waitcnt vmcnt(5)
	v_lshlrev_b32_e32 v19, 16, v32
	v_and_b32_e32 v31, 0xffff0000, v32
	v_lshlrev_b32_e32 v32, 16, v33
	v_sub_f32_e32 v47, v53, v47
	v_sub_f32_e32 v46, v52, v46
	v_and_b32_e32 v33, 0xffff0000, v33
	v_sub_f32_e32 v52, v32, v26
	v_add_co_u32_e32 v32, vcc, s18, v28
	v_cvt_pk_bf16_f32 v45, v46, v47
	v_sub_f32_e32 v47, v33, v27
	v_addc_co_u32_e32 v33, vcc, 0, v29, vcc
	global_load_dwordx4 v[26:29], v[32:33], off offset:3072
	global_load_dwordx4 v[56:59], v[32:33], off offset:2048
	v_and_b32_e32 v49, 0xffff0000, v99
	v_sub_f32_e32 v43, v49, v43
	v_cvt_pk_bf16_f32 v43, v55, v43
	v_cvt_pk_bf16_f32 v47, v52, v47
	global_load_dwordx4 v[52:55], v[32:33], off
	s_waitcnt vmcnt(7)
	v_pk_mul_f32 v[8:9], v[8:9], v[34:35] op_sel_hi:[1,0]
	v_pk_mul_f32 v[6:7], v[6:7], v[34:35] op_sel_hi:[1,0]
	v_mfma_f32_16x16x32_bf16 v[48:51], v[64:67], v[76:79], 0
	s_lshl_b64 s[18:19], s[26:27], 15
	s_add_u32 s18, s16, s18
	v_pk_mul_f32 v[16:17], v[16:17], v[34:35] op_sel_hi:[1,0]
	s_waitcnt vmcnt(4)
	v_mfma_f32_16x16x32_bf16 v[6:9], v[36:39], v[40:43], v[6:9]
	global_load_dwordx4 v[36:39], v[32:33], off offset:1024
	v_pk_mul_f32 v[14:15], v[14:15], v[34:35] op_sel_hi:[1,0]
	s_addc_u32 s19, s17, s19
	v_mfma_f32_16x16x32_bf16 v[48:51], v[68:71], v[80:83], v[48:51]
	s_lshl_b32 s20, s34, 8
	s_add_u32 s18, s18, s20
	v_sub_f32_e32 v25, v31, v25
	s_waitcnt vmcnt(2)
	v_mfma_f32_16x16x32_bf16 v[14:17], v[56:59], v[40:43], v[14:17]
	v_sub_f32_e32 v19, v19, v24
	s_addc_u32 s19, s19, 0
	v_cvt_pk_bf16_f32 v46, v19, v25
	v_mfma_f32_16x16x32_bf16 v[48:51], v[72:75], v[40:43], v[48:51]
	v_lshl_add_u64 v[24:25], s[18:19], 0, v[4:5]
	s_lshl_b64 s[18:19], s[26:27], 17
	v_pk_mul_f32 v[12:13], v[12:13], v[34:35] op_sel_hi:[1,0]
	v_pk_mul_f32 v[10:11], v[10:11], v[34:35] op_sel_hi:[1,0]
	v_mfma_f32_16x16x32_bf16 v[14:17], v[26:29], v[44:47], v[14:17]
	v_lshlrev_b32_e32 v26, 13, v1
	v_mov_b32_e32 v27, v165
	s_add_u32 s18, s54, s18
	v_mfma_f32_16x16x32_bf16 v[10:13], v[84:87], v[40:43], v[10:13]
	v_lshl_add_u64 v[24:25], v[24:25], 0, v[26:27]
	s_addc_u32 s19, s55, s19
	s_lshl_b32 s20, s34, 14
	global_store_dword v[24:25], v48, off
	global_store_dword v[24:25], v49, off offset:2048
	v_add_co_u32_e32 v24, vcc, s35, v24
	s_add_u32 s18, s18, s20
	s_nop 0
	v_addc_co_u32_e32 v25, vcc, 0, v25, vcc
	s_addc_u32 s19, s19, 0
	v_pk_mul_f32 v[22:23], v[22:23], v[34:35] op_sel_hi:[1,0]
	v_pk_mul_f32 v[20:21], v[20:21], v[34:35] op_sel_hi:[1,0]
	global_store_dword v[24:25], v50, off
	global_store_dword v[24:25], v51, off offset:2048
	v_lshl_add_u64 v[4:5], s[18:19], 0, v[4:5]
	v_lshlrev_b32_e32 v24, 10, v1
	v_mov_b32_e32 v25, v165
	v_mfma_f32_16x16x32_bf16 v[10:13], v[88:91], v[44:47], v[10:13]
	v_lshl_add_u64 v[4:5], v[4:5], 0, v[24:25]
	s_mov_b64 s[18:19], 0x1126c000
	v_lshl_add_u64 v[24:25], v[4:5], 0, s[18:19]
	s_waitcnt vmcnt(5)
	v_mfma_f32_16x16x32_bf16 v[20:23], v[52:55], v[40:43], v[20:23]
	s_mov_b32 s18, 0x1126d000
	v_add_co_u32_e32 v26, vcc, s18, v4
	v_mfma_f32_16x16x32_bf16 v[6:9], v[92:95], v[44:47], v[6:9]
	s_nop 0
	v_addc_co_u32_e32 v27, vcc, 0, v5, vcc
	s_mov_b32 s18, 0x1126e000
	s_waitcnt vmcnt(4)
	v_mfma_f32_16x16x32_bf16 v[20:23], v[36:39], v[44:47], v[20:23]
	global_store_dword v[26:27], v10, off offset:-4096
	global_store_dword v[24:25], v11, off offset:256
	global_store_dword v[24:25], v12, off offset:512
	global_store_dword v[24:25], v13, off offset:768
	global_store_dword v[26:27], v6, off
	global_store_dword v[26:27], v7, off offset:256
	global_store_dword v[26:27], v8, off offset:512
	global_store_dword v[26:27], v9, off offset:768
	v_add_co_u32_e32 v6, vcc, s18, v4
	s_mov_b32 s18, 0x1126f000
	s_nop 0
	v_addc_co_u32_e32 v7, vcc, 0, v5, vcc
	v_add_co_u32_e32 v4, vcc, s18, v4
	v_ashrrev_i32_e32 v1, 8, v35
	s_nop 0
	v_addc_co_u32_e32 v5, vcc, 0, v5, vcc
	v_add_u32_e32 v1, s28, v1
	global_store_dword v[4:5], v20, off offset:-4096
	global_store_dword v[6:7], v21, off offset:256
	global_store_dword v[6:7], v22, off offset:512
	global_store_dword v[6:7], v23, off offset:768
	global_store_dword v[4:5], v14, off
	global_store_dword v[4:5], v15, off offset:256
	global_store_dword v[4:5], v16, off offset:512
	global_store_dword v[4:5], v17, off offset:768
	v_ashrrev_i32_e32 v4, 3, v1
	v_ashrrev_i32_e32 v5, 31, v4
	v_lshrrev_b32_e32 v6, 4, v35
	v_lshlrev_b64 v[8:9], 4, v[4:5]
	v_and_or_b32 v8, v6, 15, v8
	v_lshlrev_b32_e32 v1, 6, v1
	v_lshlrev_b64 v[4:5], 11, v[8:9]
	v_and_b32_e32 v1, 0x1c0, v1
	v_lshl_add_u64 v[4:5], s[16:17], 0, v[4:5]
	v_lshlrev_b32_e32 v6, 2, v1
	v_mov_b32_e32 v7, v165
	v_lshl_add_u64 v[4:5], v[4:5], 0, v[6:7]
	v_lshlrev_b32_e32 v6, 2, v35
	v_and_b32_e32 v12, 60, v6
	v_lshlrev_b32_e32 v10, 2, v12
	v_mov_b32_e32 v11, v165
	v_lshl_add_u64 v[4:5], v[4:5], 0, v[10:11]
	s_waitcnt vmcnt(0)
	s_barrier
; __device__ __forceinline__ unsigned pk2(float lo, float hi) { return pg8::cvt_pk_bf16_v(lo, hi); }
; __device__ __forceinline__ float bflo(unsigned w) { return __uint_as_float(w << 16); }
; __device__ __forceinline__ float bfhi(unsigned w) { return __uint_as_float(w & 0xffff0000u); }
; __device__ __forceinline__ void scan_prompt_wg(const Params& P, LAS unsigned char* lds, int s, int h, int wave, int lane) {
;     ...
;         const int sl = wave, l15 = lane & 15, q4 = lane >> 4, e = 16 * sl + l15;
;         f32x4 S[4];
; #pragma unroll
;         for (int tau = 0; tau < 4; ++tau) S[tau] = (f32x4){0.f, 0.f, 0.f, 0.f};
;         const float* GT = (const float*)(P.ws + WS_GT) + (size_t)(s * 128) * 8 + h;
;         const v2u* Ug = (const v2u*)(ops0 + OPS_U) + (sl * 4) * 64 + lane;
;         v2u ua[4], ub[4];
; #pragma unroll
;         for (int tau = 0; tau < 4; ++tau) { ua[tau] = Ug[tau * 64]; ub[tau] = (Ug + step_stride / 8)[tau * 64]; }
;         SCAN_BAR();
;         int slot = 0;
;         float gt = GT[0];
; __global__ void __launch_bounds__(NWAVES * 64, 2) fwd_kernel(Params P) {
;     ...
;                 const int pr = (int)blockIdx.x * 2 + (tid >> 8), sp = pr >> 3, hp_ = pr & 7, t = (tid >> 4) & 15, part = tid & 15;
;                 const size_t row = (size_t)sp * 16 + t;
;                 const f32x4 o4 = *(const f32x4*)((const float*)(ws + WS_OAS) + row * 512 + hp_ * 64 + 4 * part);
;                 float ss = (o4[0] * o4[0] + o4[1] * o4[1]) + (o4[2] * o4[2] + o4[3] * o4[3]);
;                 ss += __shfl_xor(ss, 1); ss += __shfl_xor(ss, 2); ss += __shfl_xor(ss, 4); ss += __shfl_xor(ss, 8);
;                 const float rstd = __builtin_amdgcn_rsqf(ss * (1.0f / 64.0f) + 1e-6f);
;                 const size_t mo = ((size_t)MP + row) * 1024 + hp_ * 64 + 4 * part;
;                 const v2u zb = *(const v2u*)((const bf16*)(ws + WS_Z) + mo);
;                 const f32x4 g4 = *(const f32x4*)(P.gdn_g + 4 * part);
;                 v2u o; o.x = pk2(o4[0] * rstd * g4[0] * siluf(bflo(zb.x)), o4[1] * rstd * g4[1] * siluf(bfhi(zb.x))); o.y = pk2(o4[2] * rstd * g4[2] * siluf(bflo(zb.y)), o4[3] * rstd * g4[3] * siluf(bfhi(zb.y)));
;                 *(v2u*)((bf16*)(ws + WS_MIX) + mo) = o;
;             }
;             __syncthreads();
;             REP(30) { scan_prompt_wg(P, lds, (int)blockIdx.x >> 3, (int)blockIdx.x & 7, wave, lane); __syncthreads(); }
	global_load_dwordx4 v[4:7], v[4:5], off
	v_lshlrev_b64 v[8:9], 10, v[8:9]
	v_or3_b32 v8, v8, v1, v12
	v_mov_b64_e32 v[12:13], 0x8000000
	v_lshl_add_u64 v[12:13], v[8:9], 1, v[12:13]
	v_lshl_add_u64 v[8:9], s[10:11], 0, v[12:13]
	global_load_dwordx2 v[14:15], v[8:9], off
	v_readlane_b32 s83, v247, 18
	v_mbcnt_lo_u32_b32 v1, -1, 0
	v_mbcnt_hi_u32_b32 v1, -1, v1
	v_xor_b32_e32 v53, 1, v1
	v_xor_b32_e32 v54, 2, v1
	v_xor_b32_e32 v55, 4, v1
	global_load_dwordx4 v[8:11], v10, s[82:83]
	v_xor_b32_e32 v56, 8, v1
	v_mov_b32_e32 v19, 0x358637bd
	s_mov_b64 s[46:47], s[82:83]
	s_mov_b64 s[16:17], -1
	s_cmp_lt_i32 s33, 4
	s_mul_hi_i32 s26, s0, 0x50000
	s_mul_i32 s27, s0, 0x50000
	s_mul_i32 s28, s2, 0xa000
	v_readlane_b32 s73, v247, 8
	v_readlane_b32 s74, v247, 9
	v_readlane_b32 s75, v247, 10
	v_readlane_b32 s76, v247, 11
	v_readlane_b32 s77, v247, 12
	v_readlane_b32 s78, v247, 13
	v_readlane_b32 s79, v247, 14
	v_readlane_b32 s80, v247, 15
	v_readlane_b32 s81, v247, 16
	v_readlane_b32 s84, v247, 19
	v_readlane_b32 s85, v247, 20
	v_readlane_b32 s86, v247, 21
	v_readlane_b32 s87, v247, 22
	s_waitcnt vmcnt(2)
	v_pk_mul_f32 v[16:17], v[6:7], v[6:7]
	v_pk_mul_f32 v[20:21], v[4:5], v[4:5]
	s_nop 0
	v_pk_mov_b32 v[22:23], v[20:21], v[16:17] op_sel:[1,0]
	v_mov_b32_e32 v21, v17
	v_pk_add_f32 v[16:17], v[22:23], v[20:21]
	s_nop 0
	v_add_f32_e32 v16, v16, v17
	v_and_b32_e32 v17, 64, v1
	v_add_u32_e32 v52, 64, v17
	v_cmp_lt_i32_e32 vcc, v53, v52
	s_nop 1
	v_cndmask_b32_e32 v17, v1, v53, vcc
	v_lshlrev_b32_e32 v57, 2, v17
	ds_bpermute_b32 v17, v57, v16
	v_cmp_lt_i32_e32 vcc, v54, v52
	s_waitcnt lgkmcnt(0)
	v_add_f32_e32 v16, v16, v17
	v_cndmask_b32_e32 v17, v1, v54, vcc
	v_lshlrev_b32_e32 v58, 2, v17
	ds_bpermute_b32 v17, v58, v16
	v_cmp_lt_i32_e32 vcc, v55, v52
	s_waitcnt lgkmcnt(0)
	v_add_f32_e32 v16, v16, v17
	v_cndmask_b32_e32 v17, v1, v55, vcc
	v_lshlrev_b32_e32 v17, 2, v17
	ds_bpermute_b32 v17, v17, v16
	v_cmp_lt_i32_e32 vcc, v56, v52
	s_waitcnt lgkmcnt(0)
	v_add_f32_e32 v16, v16, v17
	v_cndmask_b32_e32 v17, v1, v56, vcc
	v_lshlrev_b32_e32 v17, 2, v17
	ds_bpermute_b32 v17, v17, v16
	s_waitcnt lgkmcnt(0)
	v_add_f32_e32 v16, v16, v17
	v_fmac_f32_e32 v19, 0x3c800000, v16
	s_waitcnt vmcnt(1)
	v_lshlrev_b32_e32 v16, 16, v14
	v_and_b32_e32 v17, 0xffff0000, v14
	v_mul_f32_e32 v14, 0xbfb8aa3b, v16
	v_exp_f32_e32 v20, v14
	v_mul_f32_e32 v14, 0xbfb8aa3b, v17
	v_exp_f32_e32 v21, v14
	v_rsq_f32_e32 v14, v19
	v_add_f32_e32 v19, 1.0, v20
	v_rcp_f32_e32 v20, v19
	v_add_f32_e32 v19, 1.0, v21
	v_rcp_f32_e32 v21, v19
	v_pk_mul_f32 v[4:5], v[4:5], v[14:15] op_sel_hi:[1,0]
	s_waitcnt vmcnt(0)
	v_pk_mul_f32 v[4:5], v[8:9], v[4:5]
	v_pk_mul_f32 v[8:9], v[20:21], v[16:17]
	v_lshlrev_b32_e32 v16, 16, v15
	v_and_b32_e32 v17, 0xffff0000, v15
	v_mul_f32_e32 v15, 0xbfb8aa3b, v16
	v_mul_f32_e32 v19, 0xbfb8aa3b, v17
	v_exp_f32_e32 v15, v15
	v_exp_f32_e32 v19, v19
	v_pk_mul_f32 v[4:5], v[4:5], v[8:9]
	v_add_f32_e32 v8, 1.0, v15
	v_add_f32_e32 v9, 1.0, v19
	v_rcp_f32_e32 v8, v8
	v_rcp_f32_e32 v9, v9
	v_pk_mul_f32 v[6:7], v[6:7], v[14:15] op_sel_hi:[1,0]
	v_cvt_pk_bf16_f32 v4, v4, v5
	v_pk_mul_f32 v[6:7], v[10:11], v[6:7]
	v_pk_mul_f32 v[8:9], v[8:9], v[16:17]
	s_nop 0
	v_pk_mul_f32 v[6:7], v[6:7], v[8:9]
	s_nop 0
	v_cvt_pk_bf16_f32 v5, v6, v7
	v_lshl_add_u64 v[6:7], s[4:5], 0, v[12:13]
	global_store_dwordx2 v[6:7], v[4:5], off
	s_barrier
	s_cbranch_scc0 .LBB0_654
	s_lshl_b32 s16, s33, 8
	s_ashr_i32 s17, s16, 31
	s_lshl_b64 s[16:17], s[16:17], 3
	s_add_u32 s18, s12, s16
	s_addc_u32 s19, s13, s17
	v_lshl_add_u64 v[4:5], s[18:19], 0, v[2:3]
	v_add_co_u32_e32 v8, vcc, s31, v4
	s_mov_b32 s19, 0x58000
	s_nop 0
	v_addc_co_u32_e32 v9, vcc, 0, v5, vcc
	v_lshl_add_u64 v[6:7], v[4:5], 0, s[24:25]
	v_add_co_u32_e32 v4, vcc, s19, v4
	s_lshl_b64 s[14:15], s[14:15], 2
	s_nop 0
	v_addc_co_u32_e32 v5, vcc, 0, v5, vcc
	global_load_dwordx2 v[50:51], v[8:9], off nt
	global_load_dwordx2 v[48:49], v[6:7], off offset:512 nt
	global_load_dwordx2 v[46:47], v[6:7], off offset:1024 nt
	global_load_dwordx2 v[44:45], v[6:7], off offset:1536 nt
	global_load_dwordx2 v[22:23], v[4:5], off nt
	global_load_dwordx2 v[24:25], v[4:5], off offset:512 nt
	global_load_dwordx2 v[26:27], v[4:5], off offset:1024 nt
	global_load_dwordx2 v[28:29], v[4:5], off offset:1536 nt
	s_add_u32 s14, s29, s14
	s_addc_u32 s15, s30, s15
	s_lshl_b32 s18, s2, 2
	s_barrier
	v_mov_b32_e32 v4, s18
	global_load_dword v34, v4, s[14:15]
	s_lshl_b64 s[0:1], s[0:1], 5
	s_or_b32 s0, s0, s18
	v_readlane_b32 s18, v247, 0
	v_readlane_b32 s19, v247, 1
	s_add_u32 s0, s18, s0
	s_addc_u32 s1, s19, s1
	s_add_u32 s14, s0, 0x1400020
	s_addc_u32 s15, s1, 0
	s_add_u32 s0, s27, s28
	s_addc_u32 s1, s26, 0
	s_add_u32 s0, s0, s16
	s_addc_u32 s1, s1, s17
	v_lshrrev_b32_e32 v4, 2, v164
	s_add_u32 s0, s18, s0
	v_and_b32_e32 v73, 12, v4
	s_addc_u32 s1, s19, s1
	v_lshl_or_b32 v20, s33, 4, v30
	v_or_b32_e32 v72, 1, v73
	v_or_b32_e32 v71, 2, v73
	v_or_b32_e32 v70, 3, v4
	v_or_b32_e32 v69, 16, v73
	v_or_b32_e32 v68, 17, v73
	v_or_b32_e32 v67, 18, v73
	v_or_b32_e32 v66, 19, v4
	v_or_b32_e32 v65, 32, v73
	v_or_b32_e32 v64, 33, v73
	v_or_b32_e32 v63, 34, v73
	v_or_b32_e32 v62, 35, v4
	v_or_b32_e32 v61, 48, v73
	v_or_b32_e32 v60, 49, v73
	v_or_b32_e32 v59, 50, v73
	v_or_b32_e32 v19, 51, v4
	v_lshl_add_u64 v[2:3], s[0:1], 0, v[2:3]
	s_mov_b64 s[0:1], 0x239a8400
	s_mov_b32 s31, 0
	v_lshl_add_u32 v21, v20, 1, 0
	v_lshlrev_b32_e32 v74, 7, v73
	v_lshlrev_b32_e32 v75, 7, v72
	v_lshlrev_b32_e32 v76, 7, v71
	v_lshlrev_b32_e32 v77, 7, v70
	v_lshlrev_b32_e32 v78, 7, v69
	v_lshlrev_b32_e32 v79, 7, v68
	v_lshlrev_b32_e32 v80, 7, v67
	v_lshlrev_b32_e32 v81, 7, v66
	v_lshlrev_b32_e32 v82, 7, v65
	v_lshlrev_b32_e32 v83, 7, v64
	v_lshlrev_b32_e32 v84, 7, v63
	v_lshlrev_b32_e32 v85, 7, v62
	v_lshlrev_b32_e32 v86, 7, v61
	v_lshlrev_b32_e32 v87, 7, v60
	v_lshlrev_b32_e32 v88, 7, v59
	v_lshlrev_b32_e32 v89, 7, v19
	v_lshl_add_u32 v90, v164, 4, 0
	v_lshl_add_u64 v[30:31], v[2:3], 0, s[0:1]
	s_mov_b32 s29, 0x1e000
	s_mov_b64 s[16:17], 0x50000
	v_mov_b32_e32 v32, 0
	s_setprio 2
	s_mov_b32 s30, 0
	v_mov_b32_e32 v14, v165
	v_mov_b32_e32 v15, v165
	v_mov_b32_e32 v16, v165
	v_mov_b32_e32 v17, v165
	v_mov_b32_e32 v10, v165
	v_mov_b32_e32 v11, v165
	v_mov_b32_e32 v12, v165
	v_mov_b32_e32 v13, v165
	v_mov_b32_e32 v2, v165
	v_mov_b32_e32 v3, v165
	v_mov_b32_e32 v4, v165
	v_mov_b32_e32 v5, v165
	v_mov_b32_e32 v6, v165
	v_mov_b32_e32 v7, v165
	v_mov_b32_e32 v8, v165
	v_mov_b32_e32 v9, v165
	s_branch .LBB0_643

; __device__ __forceinline__ void scan_prompt_wg(const Params& P, LAS unsigned char* lds, int s, int h, int wave, int lane) {
;     ...
;         float* so = P.out + O_GP + (((size_t)s * 8 + h) * 64) * 64 + e;
; #pragma unroll
;         for (int tau = 0; tau < 4; ++tau)
; #pragma unroll
;             for (int r = 0; r < 4; ++r) so[(size_t)(16 * tau + 4 * q4 + r) * 64] = S[tau][r];
.LBB0_653:
	s_setprio 0
	s_lshl_b64 s[0:1], s[8:9], 17
	s_add_u32 s0, s54, s0
	s_addc_u32 s1, s55, s1
	s_lshl_b32 s14, s2, 14
	s_add_u32 s0, s0, s14
	s_addc_u32 s1, s1, 0
	v_ashrrev_i32_e32 v21, 31, v20
	v_lshl_add_u64 v[20:21], v[20:21], 2, s[0:1]
	s_mov_b64 s[0:1], 0x10124000
	v_lshl_add_u64 v[20:21], v[20:21], 0, s[0:1]
	v_lshlrev_b32_e32 v22, 8, v73
	v_mov_b32_e32 v23, 0
	v_lshl_add_u64 v[24:25], v[20:21], 0, v[22:23]
	v_lshlrev_b32_e32 v22, 8, v72
	v_lshl_add_u64 v[26:27], v[20:21], 0, v[22:23]
	v_lshlrev_b32_e32 v22, 8, v71
	v_lshl_add_u64 v[28:29], v[20:21], 0, v[22:23]
	v_lshlrev_b32_e32 v22, 8, v70
	v_lshl_add_u64 v[30:31], v[20:21], 0, v[22:23]
	v_lshlrev_b32_e32 v22, 8, v69
	v_lshl_add_u64 v[32:33], v[20:21], 0, v[22:23]
	v_lshlrev_b32_e32 v22, 8, v68
	v_lshl_add_u64 v[36:37], v[20:21], 0, v[22:23]
	v_lshlrev_b32_e32 v22, 8, v67
	v_lshl_add_u64 v[38:39], v[20:21], 0, v[22:23]
	v_lshlrev_b32_e32 v22, 8, v66
	v_lshl_add_u64 v[40:41], v[20:21], 0, v[22:23]
	v_lshlrev_b32_e32 v22, 8, v65
	v_lshl_add_u64 v[42:43], v[20:21], 0, v[22:23]
	v_lshlrev_b32_e32 v22, 8, v64
	v_lshl_add_u64 v[44:45], v[20:21], 0, v[22:23]
	v_lshlrev_b32_e32 v22, 8, v63
	v_lshl_add_u64 v[46:47], v[20:21], 0, v[22:23]
	v_lshlrev_b32_e32 v22, 8, v62
	v_lshl_add_u64 v[48:49], v[20:21], 0, v[22:23]
	v_lshlrev_b32_e32 v22, 8, v61
	v_lshl_add_u64 v[50:51], v[20:21], 0, v[22:23]
	v_lshlrev_b32_e32 v22, 8, v60
	v_lshl_add_u64 v[60:61], v[20:21], 0, v[22:23]
	v_lshlrev_b32_e32 v22, 8, v59
	v_lshl_add_u64 v[62:63], v[20:21], 0, v[22:23]
	v_lshlrev_b32_e32 v22, 8, v19
	s_mov_b64 s[16:17], 0
	v_lshl_add_u64 v[20:21], v[20:21], 0, v[22:23]
	global_store_dword v[24:25], v14, off
	global_store_dword v[26:27], v15, off
	global_store_dword v[28:29], v16, off
	global_store_dword v[30:31], v17, off
	global_store_dword v[32:33], v10, off
	global_store_dword v[36:37], v11, off
	global_store_dword v[38:39], v12, off
	global_store_dword v[40:41], v13, off
	global_store_dword v[42:43], v2, off
	global_store_dword v[44:45], v3, off
	global_store_dword v[46:47], v4, off
	global_store_dword v[48:49], v5, off
	global_store_dword v[50:51], v6, off
	global_store_dword v[60:61], v7, off
	global_store_dword v[62:63], v8, off
	global_store_dword v[20:21], v9, off
